# v34: gate epilogue issues 7 row groups of branch-tile loads up front, sigmoids in place in acc regs
# baseline (speedup 1.0000x reference)
; __device__ __forceinline__ float lo2f(unsigned w) { return __uint_as_float(w << 16); }
; __device__ __forceinline__ float hi2f(unsigned w) { return __uint_as_float(w & 0xffff0000u); }
; __device__ __forceinline__ float sigm(float x) { return __builtin_amdgcn_rcpf(1.f + __expf(-x)); }
;   __device__ __forceinline__ void operator()(const f32x4 (&acc)[2][2][4][2], const Unit& u, int wr, int wc, int fr, int fq) const {
;     ...
;       const int q = s - 4, bjq = q >> 1, nq = q & 1;
; #pragma unroll
;       for (int ai = 0; ai < 2; ++ai)
; #pragma unroll
;         for (int m = 0; m < 4; ++m) {
;           float o[4] = {0.f, 0.f, 0.f, 0.f};
; #pragma unroll
;           for (int bj = 0; bj < 2; ++bj)
; #pragma unroll
;             for (int n = 0; n < 2; ++n) {
;               const int ib = 2 * bj + n;
;               const uint2 b2 = *(reinterpret_cast<const uint2*>(brs + (size_t)(ib * 16 + (ai * 2 + bjq) * 4 + m) * 512 + tid) + nq);
;               const f32x4 g = acc[ai][bj][m][n];
;               o[0] += sigm(g[0]) * lo2f(b2.x); o[1] += sigm(g[1]) * hi2f(b2.x);
;               o[2] += sigm(g[2]) * lo2f(b2.y); o[3] += sigm(g[3]) * hi2f(b2.y);
;             }
;           const int r = u.pm * 256 + ai * 128 + wr * 64 + m * 16 + fr;
;           const int d = dq * 256 + 64 * q + 16 * wc + 4 * fq;
;           uint2 w; w.x = pack2(o[0], o[1]); w.y = pack2(o[2], o[3]);
;           *reinterpret_cast<uint2*>(ACC + (size_t)r * 1024 + d) = w;
;         }
;     }
.LBB0_1416:
	s_mov_b32 s100, 0xbfb8aa3b
	s_add_i32 s15, s11, -4
	s_and_b32 s19, s2, 1
	s_lshl_b32 s2, s2, 5
	s_and_b32 s2, s2, 0xffffff00
	s_lshl_b32 s18, s15, 1
	s_lshl_b32 s15, s15, 6
	s_add_i32 s15, s15, s2
	s_and_b32 s14, s18, 0x7ffffffc
	s_lshl_b32 s2, s19, 3
	s_lshl_b32 s14, s14, 13
	s_add_i32 s2, s2, s14
	v_lshlrev_b32_e32 v144, 4, v140
	v_add_u32_e32 v144, s2, v144
	v_mov_b32_e32 v170, v144
	global_load_dwordx2 v[146:147], v170, s[48:49]
	v_add_u32_e32 v171, 0x20000, v144
	global_load_dwordx2 v[148:149], v171, s[48:49]
	v_add_u32_e32 v172, 0x40000, v144
	global_load_dwordx2 v[150:151], v172, s[48:49]
	v_add_u32_e32 v173, 0x60000, v144
	global_load_dwordx2 v[152:153], v173, s[48:49]
	v_add_u32_e32 v170, 0x2000, v144
	global_load_dwordx2 v[154:155], v170, s[48:49]
	v_add_u32_e32 v171, 0x22000, v144
	global_load_dwordx2 v[156:157], v171, s[48:49]
	v_add_u32_e32 v172, 0x42000, v144
	global_load_dwordx2 v[158:159], v172, s[48:49]
	v_add_u32_e32 v173, 0x62000, v144
	global_load_dwordx2 v[160:161], v173, s[48:49]
	v_add_u32_e32 v170, 0x4000, v144
	global_load_dwordx2 v[162:163], v170, s[48:49]
	v_add_u32_e32 v171, 0x24000, v144
	global_load_dwordx2 v[164:165], v171, s[48:49]
	v_add_u32_e32 v172, 0x44000, v144
	global_load_dwordx2 v[166:167], v172, s[48:49]
	v_add_u32_e32 v173, 0x64000, v144
	global_load_dwordx2 v[168:169], v173, s[48:49]
	v_add_u32_e32 v170, 0x6000, v144
	global_load_dwordx2 v[202:203], v170, s[48:49]
	v_add_u32_e32 v171, 0x26000, v144
	global_load_dwordx2 v[204:205], v171, s[48:49]
	v_add_u32_e32 v172, 0x46000, v144
	global_load_dwordx2 v[206:207], v172, s[48:49]
	v_add_u32_e32 v173, 0x66000, v144
	global_load_dwordx2 v[208:209], v173, s[48:49]
	v_add_u32_e32 v170, 0x10000, v144
	global_load_dwordx2 v[210:211], v170, s[48:49]
	v_add_u32_e32 v171, 0x30000, v144
	global_load_dwordx2 v[212:213], v171, s[48:49]
	v_add_u32_e32 v172, 0x50000, v144
	global_load_dwordx2 v[214:215], v172, s[48:49]
	v_add_u32_e32 v173, 0x70000, v144
	global_load_dwordx2 v[216:217], v173, s[48:49]
	v_add_u32_e32 v170, 0x12000, v144
	global_load_dwordx2 v[234:235], v170, s[48:49]
	v_add_u32_e32 v171, 0x32000, v144
	global_load_dwordx2 v[236:237], v171, s[48:49]
	v_add_u32_e32 v172, 0x52000, v144
	global_load_dwordx2 v[238:239], v172, s[48:49]
	v_add_u32_e32 v173, 0x72000, v144
	global_load_dwordx2 v[240:241], v173, s[48:49]
	v_add_u32_e32 v170, 0x14000, v144
	global_load_dwordx2 v[242:243], v170, s[48:49]
	v_add_u32_e32 v171, 0x34000, v144
	global_load_dwordx2 v[244:245], v171, s[48:49]
	v_add_u32_e32 v172, 0x54000, v144
	global_load_dwordx2 v[246:247], v172, s[48:49]
	v_add_u32_e32 v173, 0x74000, v144
	global_load_dwordx2 v[248:249], v173, s[48:49]
	v_or_b32_e32 v145, s15, v200
	v_lshl_add_u32 v143, s16, 8, v1
	v_lshlrev_b32_e32 v145, 1, v145
	v_lshl_add_u32 v145, v143, 11, v145
	v_pk_mul_f32 v[174:175], v[126:127], s[100:101] op_sel_hi:[1,0]
	v_pk_mul_f32 v[182:183], v[128:129], s[100:101] op_sel_hi:[1,0]
	v_exp_f32_e32 v174, v174
	v_exp_f32_e32 v175, v175
	v_exp_f32_e32 v182, v182
	v_exp_f32_e32 v183, v183
	v_pk_add_f32 v[174:175], v[174:175], 1.0 op_sel_hi:[1,0]
	v_pk_add_f32 v[182:183], v[182:183], 1.0 op_sel_hi:[1,0]
	v_rcp_f32_e32 v126, v174
	v_rcp_f32_e32 v127, v175
	v_rcp_f32_e32 v128, v182
	v_rcp_f32_e32 v129, v183
	v_pk_mul_f32 v[174:175], v[122:123], s[100:101] op_sel_hi:[1,0]
	v_pk_mul_f32 v[182:183], v[124:125], s[100:101] op_sel_hi:[1,0]
	v_exp_f32_e32 v174, v174
	v_exp_f32_e32 v175, v175
	v_exp_f32_e32 v182, v182
	v_exp_f32_e32 v183, v183
	v_pk_add_f32 v[174:175], v[174:175], 1.0 op_sel_hi:[1,0]
	v_pk_add_f32 v[182:183], v[182:183], 1.0 op_sel_hi:[1,0]
	v_rcp_f32_e32 v122, v174
	v_rcp_f32_e32 v123, v175
	v_rcp_f32_e32 v124, v182
	v_rcp_f32_e32 v125, v183
	v_pk_mul_f32 v[174:175], v[94:95], s[100:101] op_sel_hi:[1,0]
	v_pk_mul_f32 v[182:183], v[96:97], s[100:101] op_sel_hi:[1,0]
	v_exp_f32_e32 v174, v174
	v_exp_f32_e32 v175, v175
	v_exp_f32_e32 v182, v182
	v_exp_f32_e32 v183, v183
	v_pk_add_f32 v[174:175], v[174:175], 1.0 op_sel_hi:[1,0]
	v_pk_add_f32 v[182:183], v[182:183], 1.0 op_sel_hi:[1,0]
	v_rcp_f32_e32 v94, v174
	v_rcp_f32_e32 v95, v175
	v_rcp_f32_e32 v96, v182
	v_rcp_f32_e32 v97, v183
	v_pk_mul_f32 v[174:175], v[90:91], s[100:101] op_sel_hi:[1,0]
	v_pk_mul_f32 v[182:183], v[92:93], s[100:101] op_sel_hi:[1,0]
	v_exp_f32_e32 v174, v174
	v_exp_f32_e32 v175, v175
	v_exp_f32_e32 v182, v182
	v_exp_f32_e32 v183, v183
	v_pk_add_f32 v[174:175], v[174:175], 1.0 op_sel_hi:[1,0]
	v_pk_add_f32 v[182:183], v[182:183], 1.0 op_sel_hi:[1,0]
	v_rcp_f32_e32 v90, v174
	v_rcp_f32_e32 v91, v175
	v_rcp_f32_e32 v92, v182
	v_rcp_f32_e32 v93, v183
	v_pk_mul_f32 v[174:175], v[118:119], s[100:101] op_sel_hi:[1,0]
	v_pk_mul_f32 v[182:183], v[120:121], s[100:101] op_sel_hi:[1,0]
	v_exp_f32_e32 v174, v174
	v_exp_f32_e32 v175, v175
	v_exp_f32_e32 v182, v182
	v_exp_f32_e32 v183, v183
	v_pk_add_f32 v[174:175], v[174:175], 1.0 op_sel_hi:[1,0]
	v_pk_add_f32 v[182:183], v[182:183], 1.0 op_sel_hi:[1,0]
	v_rcp_f32_e32 v118, v174
	v_rcp_f32_e32 v119, v175
	v_rcp_f32_e32 v120, v182
	v_rcp_f32_e32 v121, v183
	v_pk_mul_f32 v[174:175], v[114:115], s[100:101] op_sel_hi:[1,0]
	v_pk_mul_f32 v[182:183], v[116:117], s[100:101] op_sel_hi:[1,0]
	v_exp_f32_e32 v174, v174
	v_exp_f32_e32 v175, v175
	v_exp_f32_e32 v182, v182
	v_exp_f32_e32 v183, v183
	v_pk_add_f32 v[174:175], v[174:175], 1.0 op_sel_hi:[1,0]
	v_pk_add_f32 v[182:183], v[182:183], 1.0 op_sel_hi:[1,0]
	v_rcp_f32_e32 v114, v174
	v_rcp_f32_e32 v115, v175
	v_rcp_f32_e32 v116, v182
	v_rcp_f32_e32 v117, v183
	v_pk_mul_f32 v[174:175], v[86:87], s[100:101] op_sel_hi:[1,0]
	v_pk_mul_f32 v[182:183], v[88:89], s[100:101] op_sel_hi:[1,0]
; __device__ __forceinline__ float lo2f(unsigned w) { return __uint_as_float(w << 16); }
; __device__ __forceinline__ float hi2f(unsigned w) { return __uint_as_float(w & 0xffff0000u); }
; __device__ __forceinline__ float sigm(float x) { return __builtin_amdgcn_rcpf(1.f + __expf(-x)); }
;   __device__ __forceinline__ void operator()(const f32x4 (&acc)[2][2][4][2], const Unit& u, int wr, int wc, int fr, int fq) const {
;     ...
;       const int q = s - 4, bjq = q >> 1, nq = q & 1;
; #pragma unroll
;       for (int ai = 0; ai < 2; ++ai)
; #pragma unroll
;         for (int m = 0; m < 4; ++m) {
;           float o[4] = {0.f, 0.f, 0.f, 0.f};
; #pragma unroll
;           for (int bj = 0; bj < 2; ++bj)
; #pragma unroll
;             for (int n = 0; n < 2; ++n) {
;               const int ib = 2 * bj + n;
;               const uint2 b2 = *(reinterpret_cast<const uint2*>(brs + (size_t)(ib * 16 + (ai * 2 + bjq) * 4 + m) * 512 + tid) + nq);
;               const f32x4 g = acc[ai][bj][m][n];
;               o[0] += sigm(g[0]) * lo2f(b2.x); o[1] += sigm(g[1]) * hi2f(b2.x);
;               o[2] += sigm(g[2]) * lo2f(b2.y); o[3] += sigm(g[3]) * hi2f(b2.y);
;             }
;           const int r = u.pm * 256 + ai * 128 + wr * 64 + m * 16 + fr;
;           const int d = dq * 256 + 64 * q + 16 * wc + 4 * fq;
;           uint2 w; w.x = pack2(o[0], o[1]); w.y = pack2(o[2], o[3]);
;           *reinterpret_cast<uint2*>(ACC + (size_t)r * 1024 + d) = w;
;         }
;     }
	v_exp_f32_e32 v174, v174
	v_exp_f32_e32 v175, v175
	v_exp_f32_e32 v182, v182
	v_exp_f32_e32 v183, v183
	v_pk_add_f32 v[174:175], v[174:175], 1.0 op_sel_hi:[1,0]
	v_pk_add_f32 v[182:183], v[182:183], 1.0 op_sel_hi:[1,0]
	v_rcp_f32_e32 v86, v174
	v_rcp_f32_e32 v87, v175
	v_rcp_f32_e32 v88, v182
	v_rcp_f32_e32 v89, v183
	v_pk_mul_f32 v[174:175], v[82:83], s[100:101] op_sel_hi:[1,0]
	v_pk_mul_f32 v[182:183], v[84:85], s[100:101] op_sel_hi:[1,0]
	v_exp_f32_e32 v174, v174
	v_exp_f32_e32 v175, v175
	v_exp_f32_e32 v182, v182
	v_exp_f32_e32 v183, v183
	v_pk_add_f32 v[174:175], v[174:175], 1.0 op_sel_hi:[1,0]
	v_pk_add_f32 v[182:183], v[182:183], 1.0 op_sel_hi:[1,0]
	v_rcp_f32_e32 v82, v174
	v_rcp_f32_e32 v83, v175
	v_rcp_f32_e32 v84, v182
	v_rcp_f32_e32 v85, v183
	v_pk_mul_f32 v[174:175], v[110:111], s[100:101] op_sel_hi:[1,0]
	v_pk_mul_f32 v[182:183], v[112:113], s[100:101] op_sel_hi:[1,0]
	v_exp_f32_e32 v174, v174
	v_exp_f32_e32 v175, v175
	v_exp_f32_e32 v182, v182
	v_exp_f32_e32 v183, v183
	v_pk_add_f32 v[174:175], v[174:175], 1.0 op_sel_hi:[1,0]
	v_pk_add_f32 v[182:183], v[182:183], 1.0 op_sel_hi:[1,0]
	v_rcp_f32_e32 v110, v174
	v_rcp_f32_e32 v111, v175
	v_rcp_f32_e32 v112, v182
	v_rcp_f32_e32 v113, v183
	v_pk_mul_f32 v[174:175], v[106:107], s[100:101] op_sel_hi:[1,0]
	v_pk_mul_f32 v[182:183], v[108:109], s[100:101] op_sel_hi:[1,0]
	v_exp_f32_e32 v174, v174
	v_exp_f32_e32 v175, v175
	v_exp_f32_e32 v182, v182
	v_exp_f32_e32 v183, v183
	v_pk_add_f32 v[174:175], v[174:175], 1.0 op_sel_hi:[1,0]
	v_pk_add_f32 v[182:183], v[182:183], 1.0 op_sel_hi:[1,0]
	v_rcp_f32_e32 v106, v174
	v_rcp_f32_e32 v107, v175
	v_rcp_f32_e32 v108, v182
	v_rcp_f32_e32 v109, v183
	v_pk_mul_f32 v[174:175], v[78:79], s[100:101] op_sel_hi:[1,0]
	v_pk_mul_f32 v[182:183], v[80:81], s[100:101] op_sel_hi:[1,0]
	v_exp_f32_e32 v174, v174
	v_exp_f32_e32 v175, v175
	v_exp_f32_e32 v182, v182
	v_exp_f32_e32 v183, v183
	v_pk_add_f32 v[174:175], v[174:175], 1.0 op_sel_hi:[1,0]
	v_pk_add_f32 v[182:183], v[182:183], 1.0 op_sel_hi:[1,0]
	v_rcp_f32_e32 v78, v174
	v_rcp_f32_e32 v79, v175
	v_rcp_f32_e32 v80, v182
	v_rcp_f32_e32 v81, v183
	v_pk_mul_f32 v[174:175], v[74:75], s[100:101] op_sel_hi:[1,0]
	v_pk_mul_f32 v[182:183], v[76:77], s[100:101] op_sel_hi:[1,0]
	v_exp_f32_e32 v174, v174
	v_exp_f32_e32 v175, v175
	v_exp_f32_e32 v182, v182
	v_exp_f32_e32 v183, v183
	v_pk_add_f32 v[174:175], v[174:175], 1.0 op_sel_hi:[1,0]
	v_pk_add_f32 v[182:183], v[182:183], 1.0 op_sel_hi:[1,0]
	v_rcp_f32_e32 v74, v174
	v_rcp_f32_e32 v75, v175
	v_rcp_f32_e32 v76, v182
	v_rcp_f32_e32 v77, v183
	v_pk_mul_f32 v[174:175], v[102:103], s[100:101] op_sel_hi:[1,0]
	v_pk_mul_f32 v[182:183], v[104:105], s[100:101] op_sel_hi:[1,0]
	v_exp_f32_e32 v174, v174
	v_exp_f32_e32 v175, v175
	v_exp_f32_e32 v182, v182
	v_exp_f32_e32 v183, v183
	v_pk_add_f32 v[174:175], v[174:175], 1.0 op_sel_hi:[1,0]
	v_pk_add_f32 v[182:183], v[182:183], 1.0 op_sel_hi:[1,0]
	v_rcp_f32_e32 v102, v174
	v_rcp_f32_e32 v103, v175
	v_rcp_f32_e32 v104, v182
	v_rcp_f32_e32 v105, v183
	v_pk_mul_f32 v[174:175], v[98:99], s[100:101] op_sel_hi:[1,0]
	v_pk_mul_f32 v[182:183], v[100:101], s[100:101] op_sel_hi:[1,0]
	v_exp_f32_e32 v174, v174
	v_exp_f32_e32 v175, v175
	v_exp_f32_e32 v182, v182
	v_exp_f32_e32 v183, v183
	v_pk_add_f32 v[174:175], v[174:175], 1.0 op_sel_hi:[1,0]
	v_pk_add_f32 v[182:183], v[182:183], 1.0 op_sel_hi:[1,0]
	v_rcp_f32_e32 v98, v174
	v_rcp_f32_e32 v99, v175
	v_rcp_f32_e32 v100, v182
	v_rcp_f32_e32 v101, v183
	v_pk_mul_f32 v[174:175], v[70:71], s[100:101] op_sel_hi:[1,0]
	v_pk_mul_f32 v[182:183], v[72:73], s[100:101] op_sel_hi:[1,0]
	v_exp_f32_e32 v174, v174
	v_exp_f32_e32 v175, v175
	v_exp_f32_e32 v182, v182
	v_exp_f32_e32 v183, v183
	v_pk_add_f32 v[174:175], v[174:175], 1.0 op_sel_hi:[1,0]
	v_pk_add_f32 v[182:183], v[182:183], 1.0 op_sel_hi:[1,0]
	v_rcp_f32_e32 v70, v174
	v_rcp_f32_e32 v71, v175
	v_rcp_f32_e32 v72, v182
	v_rcp_f32_e32 v73, v183
	v_pk_mul_f32 v[174:175], v[66:67], s[100:101] op_sel_hi:[1,0]
	v_pk_mul_f32 v[182:183], v[68:69], s[100:101] op_sel_hi:[1,0]
	v_exp_f32_e32 v174, v174
	v_exp_f32_e32 v175, v175
	v_exp_f32_e32 v182, v182
	v_exp_f32_e32 v183, v183
	v_pk_add_f32 v[174:175], v[174:175], 1.0 op_sel_hi:[1,0]
	v_pk_add_f32 v[182:183], v[182:183], 1.0 op_sel_hi:[1,0]
	v_rcp_f32_e32 v66, v174
	v_rcp_f32_e32 v67, v175
	v_rcp_f32_e32 v68, v182
	v_rcp_f32_e32 v69, v183
	v_pk_mul_f32 v[174:175], v[62:63], s[100:101] op_sel_hi:[1,0]
	v_pk_mul_f32 v[182:183], v[64:65], s[100:101] op_sel_hi:[1,0]
	v_exp_f32_e32 v174, v174
	v_exp_f32_e32 v175, v175
	v_exp_f32_e32 v182, v182
	v_exp_f32_e32 v183, v183
	v_pk_add_f32 v[174:175], v[174:175], 1.0 op_sel_hi:[1,0]
	v_pk_add_f32 v[182:183], v[182:183], 1.0 op_sel_hi:[1,0]
	v_rcp_f32_e32 v62, v174
	v_rcp_f32_e32 v63, v175
	v_rcp_f32_e32 v64, v182
	v_rcp_f32_e32 v65, v183
	v_pk_mul_f32 v[174:175], v[58:59], s[100:101] op_sel_hi:[1,0]
	v_pk_mul_f32 v[182:183], v[60:61], s[100:101] op_sel_hi:[1,0]
	v_exp_f32_e32 v174, v174
	v_exp_f32_e32 v175, v175
	v_exp_f32_e32 v182, v182
	v_exp_f32_e32 v183, v183
	v_pk_add_f32 v[174:175], v[174:175], 1.0 op_sel_hi:[1,0]
	v_pk_add_f32 v[182:183], v[182:183], 1.0 op_sel_hi:[1,0]
	v_rcp_f32_e32 v58, v174
	v_rcp_f32_e32 v59, v175
	v_rcp_f32_e32 v60, v182
	v_rcp_f32_e32 v61, v183
	v_pk_mul_f32 v[174:175], v[30:31], s[100:101] op_sel_hi:[1,0]
	v_pk_mul_f32 v[182:183], v[32:33], s[100:101] op_sel_hi:[1,0]
	v_exp_f32_e32 v174, v174
	v_exp_f32_e32 v175, v175
	v_exp_f32_e32 v182, v182
	v_exp_f32_e32 v183, v183
	v_pk_add_f32 v[174:175], v[174:175], 1.0 op_sel_hi:[1,0]
	v_pk_add_f32 v[182:183], v[182:183], 1.0 op_sel_hi:[1,0]
	v_rcp_f32_e32 v30, v174
	v_rcp_f32_e32 v31, v175
; __device__ __forceinline__ float lo2f(unsigned w) { return __uint_as_float(w << 16); }
; __device__ __forceinline__ float hi2f(unsigned w) { return __uint_as_float(w & 0xffff0000u); }
; __device__ __forceinline__ float sigm(float x) { return __builtin_amdgcn_rcpf(1.f + __expf(-x)); }
;   __device__ __forceinline__ void operator()(const f32x4 (&acc)[2][2][4][2], const Unit& u, int wr, int wc, int fr, int fq) const {
;     ...
;       const int q = s - 4, bjq = q >> 1, nq = q & 1;
; #pragma unroll
;       for (int ai = 0; ai < 2; ++ai)
; #pragma unroll
;         for (int m = 0; m < 4; ++m) {
;           float o[4] = {0.f, 0.f, 0.f, 0.f};
; #pragma unroll
;           for (int bj = 0; bj < 2; ++bj)
; #pragma unroll
;             for (int n = 0; n < 2; ++n) {
;               const int ib = 2 * bj + n;
;               const uint2 b2 = *(reinterpret_cast<const uint2*>(brs + (size_t)(ib * 16 + (ai * 2 + bjq) * 4 + m) * 512 + tid) + nq);
;               const f32x4 g = acc[ai][bj][m][n];
;               o[0] += sigm(g[0]) * lo2f(b2.x); o[1] += sigm(g[1]) * hi2f(b2.x);
;               o[2] += sigm(g[2]) * lo2f(b2.y); o[3] += sigm(g[3]) * hi2f(b2.y);
;             }
;           const int r = u.pm * 256 + ai * 128 + wr * 64 + m * 16 + fr;
;           const int d = dq * 256 + 64 * q + 16 * wc + 4 * fq;
;           uint2 w; w.x = pack2(o[0], o[1]); w.y = pack2(o[2], o[3]);
;           *reinterpret_cast<uint2*>(ACC + (size_t)r * 1024 + d) = w;
;         }
;     }
	v_rcp_f32_e32 v32, v182
	v_rcp_f32_e32 v33, v183
	v_pk_mul_f32 v[174:175], v[26:27], s[100:101] op_sel_hi:[1,0]
	v_pk_mul_f32 v[182:183], v[28:29], s[100:101] op_sel_hi:[1,0]
	v_exp_f32_e32 v174, v174
	v_exp_f32_e32 v175, v175
	v_exp_f32_e32 v182, v182
	v_exp_f32_e32 v183, v183
	v_pk_add_f32 v[174:175], v[174:175], 1.0 op_sel_hi:[1,0]
	v_pk_add_f32 v[182:183], v[182:183], 1.0 op_sel_hi:[1,0]
	v_rcp_f32_e32 v26, v174
	v_rcp_f32_e32 v27, v175
	v_rcp_f32_e32 v28, v182
	v_rcp_f32_e32 v29, v183
	v_pk_mul_f32 v[174:175], v[54:55], s[100:101] op_sel_hi:[1,0]
	v_pk_mul_f32 v[182:183], v[56:57], s[100:101] op_sel_hi:[1,0]
	v_exp_f32_e32 v174, v174
	v_exp_f32_e32 v175, v175
	v_exp_f32_e32 v182, v182
	v_exp_f32_e32 v183, v183
	v_pk_add_f32 v[174:175], v[174:175], 1.0 op_sel_hi:[1,0]
	v_pk_add_f32 v[182:183], v[182:183], 1.0 op_sel_hi:[1,0]
	v_rcp_f32_e32 v54, v174
	v_rcp_f32_e32 v55, v175
	v_rcp_f32_e32 v56, v182
	v_rcp_f32_e32 v57, v183
	v_pk_mul_f32 v[174:175], v[50:51], s[100:101] op_sel_hi:[1,0]
	v_pk_mul_f32 v[182:183], v[52:53], s[100:101] op_sel_hi:[1,0]
	v_exp_f32_e32 v174, v174
	v_exp_f32_e32 v175, v175
	v_exp_f32_e32 v182, v182
	v_exp_f32_e32 v183, v183
	v_pk_add_f32 v[174:175], v[174:175], 1.0 op_sel_hi:[1,0]
	v_pk_add_f32 v[182:183], v[182:183], 1.0 op_sel_hi:[1,0]
	v_rcp_f32_e32 v50, v174
	v_rcp_f32_e32 v51, v175
	v_rcp_f32_e32 v52, v182
	v_rcp_f32_e32 v53, v183
	v_pk_mul_f32 v[174:175], v[22:23], s[100:101] op_sel_hi:[1,0]
	v_pk_mul_f32 v[182:183], v[24:25], s[100:101] op_sel_hi:[1,0]
	v_exp_f32_e32 v174, v174
	v_exp_f32_e32 v175, v175
	v_exp_f32_e32 v182, v182
	v_exp_f32_e32 v183, v183
	v_pk_add_f32 v[174:175], v[174:175], 1.0 op_sel_hi:[1,0]
	v_pk_add_f32 v[182:183], v[182:183], 1.0 op_sel_hi:[1,0]
	v_rcp_f32_e32 v22, v174
	v_rcp_f32_e32 v23, v175
	v_rcp_f32_e32 v24, v182
	v_rcp_f32_e32 v25, v183
	v_pk_mul_f32 v[174:175], v[18:19], s[100:101] op_sel_hi:[1,0]
	v_pk_mul_f32 v[182:183], v[20:21], s[100:101] op_sel_hi:[1,0]
	v_exp_f32_e32 v174, v174
	v_exp_f32_e32 v175, v175
	v_exp_f32_e32 v182, v182
	v_exp_f32_e32 v183, v183
	v_pk_add_f32 v[174:175], v[174:175], 1.0 op_sel_hi:[1,0]
	v_pk_add_f32 v[182:183], v[182:183], 1.0 op_sel_hi:[1,0]
	v_rcp_f32_e32 v18, v174
	v_rcp_f32_e32 v19, v175
	v_rcp_f32_e32 v20, v182
	v_rcp_f32_e32 v21, v183
	v_pk_mul_f32 v[174:175], v[46:47], s[100:101] op_sel_hi:[1,0]
	v_pk_mul_f32 v[182:183], v[48:49], s[100:101] op_sel_hi:[1,0]
	v_exp_f32_e32 v174, v174
	v_exp_f32_e32 v175, v175
	v_exp_f32_e32 v182, v182
	v_exp_f32_e32 v183, v183
	v_pk_add_f32 v[174:175], v[174:175], 1.0 op_sel_hi:[1,0]
	v_pk_add_f32 v[182:183], v[182:183], 1.0 op_sel_hi:[1,0]
	v_rcp_f32_e32 v46, v174
	v_rcp_f32_e32 v47, v175
	v_rcp_f32_e32 v48, v182
	v_rcp_f32_e32 v49, v183
	v_pk_mul_f32 v[174:175], v[42:43], s[100:101] op_sel_hi:[1,0]
	v_pk_mul_f32 v[182:183], v[44:45], s[100:101] op_sel_hi:[1,0]
	v_exp_f32_e32 v174, v174
	v_exp_f32_e32 v175, v175
	v_exp_f32_e32 v182, v182
	v_exp_f32_e32 v183, v183
	v_pk_add_f32 v[174:175], v[174:175], 1.0 op_sel_hi:[1,0]
	v_pk_add_f32 v[182:183], v[182:183], 1.0 op_sel_hi:[1,0]
	v_rcp_f32_e32 v42, v174
	v_rcp_f32_e32 v43, v175
	v_rcp_f32_e32 v44, v182
	v_rcp_f32_e32 v45, v183
	v_pk_mul_f32 v[174:175], v[14:15], s[100:101] op_sel_hi:[1,0]
	v_pk_mul_f32 v[182:183], v[16:17], s[100:101] op_sel_hi:[1,0]
	v_exp_f32_e32 v174, v174
	v_exp_f32_e32 v175, v175
	v_exp_f32_e32 v182, v182
	v_exp_f32_e32 v183, v183
	v_pk_add_f32 v[174:175], v[174:175], 1.0 op_sel_hi:[1,0]
	v_pk_add_f32 v[182:183], v[182:183], 1.0 op_sel_hi:[1,0]
	v_rcp_f32_e32 v14, v174
	v_rcp_f32_e32 v15, v175
	v_rcp_f32_e32 v16, v182
	v_rcp_f32_e32 v17, v183
	v_pk_mul_f32 v[174:175], v[10:11], s[100:101] op_sel_hi:[1,0]
	v_pk_mul_f32 v[182:183], v[12:13], s[100:101] op_sel_hi:[1,0]
	v_exp_f32_e32 v174, v174
	v_exp_f32_e32 v175, v175
	v_exp_f32_e32 v182, v182
	v_exp_f32_e32 v183, v183
	v_pk_add_f32 v[174:175], v[174:175], 1.0 op_sel_hi:[1,0]
	v_pk_add_f32 v[182:183], v[182:183], 1.0 op_sel_hi:[1,0]
	v_rcp_f32_e32 v10, v174
	v_rcp_f32_e32 v11, v175
	v_rcp_f32_e32 v12, v182
	v_rcp_f32_e32 v13, v183
	v_pk_mul_f32 v[174:175], v[38:39], s[100:101] op_sel_hi:[1,0]
	v_pk_mul_f32 v[182:183], v[40:41], s[100:101] op_sel_hi:[1,0]
	v_exp_f32_e32 v174, v174
	v_exp_f32_e32 v175, v175
	v_exp_f32_e32 v182, v182
	v_exp_f32_e32 v183, v183
	v_pk_add_f32 v[174:175], v[174:175], 1.0 op_sel_hi:[1,0]
	v_pk_add_f32 v[182:183], v[182:183], 1.0 op_sel_hi:[1,0]
	v_rcp_f32_e32 v38, v174
	v_rcp_f32_e32 v39, v175
	v_rcp_f32_e32 v40, v182
	v_rcp_f32_e32 v41, v183
	v_pk_mul_f32 v[174:175], v[34:35], s[100:101] op_sel_hi:[1,0]
	v_pk_mul_f32 v[182:183], v[36:37], s[100:101] op_sel_hi:[1,0]
	v_exp_f32_e32 v174, v174
	v_exp_f32_e32 v175, v175
	v_exp_f32_e32 v182, v182
	v_exp_f32_e32 v183, v183
	v_pk_add_f32 v[174:175], v[174:175], 1.0 op_sel_hi:[1,0]
	v_pk_add_f32 v[182:183], v[182:183], 1.0 op_sel_hi:[1,0]
	v_rcp_f32_e32 v34, v174
	v_rcp_f32_e32 v35, v175
	v_rcp_f32_e32 v36, v182
	v_rcp_f32_e32 v37, v183
	v_pk_mul_f32 v[174:175], v[6:7], s[100:101] op_sel_hi:[1,0]
	v_pk_mul_f32 v[182:183], v[8:9], s[100:101] op_sel_hi:[1,0]
	v_exp_f32_e32 v174, v174
	v_exp_f32_e32 v175, v175
	v_exp_f32_e32 v182, v182
	v_exp_f32_e32 v183, v183
	v_pk_add_f32 v[174:175], v[174:175], 1.0 op_sel_hi:[1,0]
	v_pk_add_f32 v[182:183], v[182:183], 1.0 op_sel_hi:[1,0]
	v_rcp_f32_e32 v6, v174
	v_rcp_f32_e32 v7, v175
	v_rcp_f32_e32 v8, v182
	v_rcp_f32_e32 v9, v183
	v_pk_mul_f32 v[174:175], v[2:3], s[100:101] op_sel_hi:[1,0]
	v_pk_mul_f32 v[182:183], v[4:5], s[100:101] op_sel_hi:[1,0]
	v_exp_f32_e32 v174, v174
	v_exp_f32_e32 v175, v175
	v_exp_f32_e32 v182, v182
	v_exp_f32_e32 v183, v183
	v_pk_add_f32 v[174:175], v[174:175], 1.0 op_sel_hi:[1,0]
	v_pk_add_f32 v[182:183], v[182:183], 1.0 op_sel_hi:[1,0]
	v_rcp_f32_e32 v2, v174
	v_rcp_f32_e32 v3, v175
	v_rcp_f32_e32 v4, v182
	v_rcp_f32_e32 v5, v183
	s_waitcnt vmcnt(24)
; __device__ __forceinline__ float lo2f(unsigned w) { return __uint_as_float(w << 16); }
; __device__ __forceinline__ float hi2f(unsigned w) { return __uint_as_float(w & 0xffff0000u); }
; __device__ __forceinline__ float sigm(float x) { return __builtin_amdgcn_rcpf(1.f + __expf(-x)); }
;   __device__ __forceinline__ void operator()(const f32x4 (&acc)[2][2][4][2], const Unit& u, int wr, int wc, int fr, int fq) const {
;     ...
;       const int q = s - 4, bjq = q >> 1, nq = q & 1;
; #pragma unroll
;       for (int ai = 0; ai < 2; ++ai)
; #pragma unroll
;         for (int m = 0; m < 4; ++m) {
;           float o[4] = {0.f, 0.f, 0.f, 0.f};
; #pragma unroll
;           for (int bj = 0; bj < 2; ++bj)
; #pragma unroll
;             for (int n = 0; n < 2; ++n) {
;               const int ib = 2 * bj + n;
;               const uint2 b2 = *(reinterpret_cast<const uint2*>(brs + (size_t)(ib * 16 + (ai * 2 + bjq) * 4 + m) * 512 + tid) + nq);
;               const f32x4 g = acc[ai][bj][m][n];
;               o[0] += sigm(g[0]) * lo2f(b2.x); o[1] += sigm(g[1]) * hi2f(b2.x);
;               o[2] += sigm(g[2]) * lo2f(b2.y); o[3] += sigm(g[3]) * hi2f(b2.y);
;             }
;           const int r = u.pm * 256 + ai * 128 + wr * 64 + m * 16 + fr;
;           const int d = dq * 256 + 64 * q + 16 * wc + 4 * fq;
;           uint2 w; w.x = pack2(o[0], o[1]); w.y = pack2(o[2], o[3]);
;           *reinterpret_cast<uint2*>(ACC + (size_t)r * 1024 + d) = w;
;         }
;     }
	v_lshlrev_b32_e32 v218, 16, v146
	v_and_b32_e32 v219, 0xffff0000, v146
	v_lshlrev_b32_e32 v220, 16, v147
	v_and_b32_e32 v221, 0xffff0000, v147
	v_pk_fma_f32 v[222:223], v[126:127], v[218:219], 0 op_sel_hi:[1,1,0]
	v_pk_fma_f32 v[224:225], v[128:129], v[220:221], 0 op_sel_hi:[1,1,0]
	v_lshlrev_b32_e32 v218, 16, v148
	v_and_b32_e32 v219, 0xffff0000, v148
	v_lshlrev_b32_e32 v220, 16, v149
	v_and_b32_e32 v221, 0xffff0000, v149
	v_pk_fma_f32 v[222:223], v[122:123], v[218:219], v[222:223]
	v_pk_fma_f32 v[224:225], v[124:125], v[220:221], v[224:225]
	v_lshlrev_b32_e32 v218, 16, v150
	v_and_b32_e32 v219, 0xffff0000, v150
	v_lshlrev_b32_e32 v220, 16, v151
	v_and_b32_e32 v221, 0xffff0000, v151
	v_pk_fma_f32 v[222:223], v[94:95], v[218:219], v[222:223]
	v_pk_fma_f32 v[224:225], v[96:97], v[220:221], v[224:225]
	v_lshlrev_b32_e32 v218, 16, v152
	v_and_b32_e32 v219, 0xffff0000, v152
	v_lshlrev_b32_e32 v220, 16, v153
	v_and_b32_e32 v221, 0xffff0000, v153
	v_pk_fma_f32 v[222:223], v[90:91], v[218:219], v[222:223]
	v_pk_fma_f32 v[224:225], v[92:93], v[220:221], v[224:225]
	v_add_u32_e32 v170, 0x16000, v144
	global_load_dwordx2 v[146:147], v170, s[48:49]
	v_add_u32_e32 v171, 0x36000, v144
	global_load_dwordx2 v[148:149], v171, s[48:49]
	v_add_u32_e32 v172, 0x56000, v144
	global_load_dwordx2 v[150:151], v172, s[48:49]
	v_add_u32_e32 v173, 0x76000, v144
	global_load_dwordx2 v[152:153], v173, s[48:49]
	v_mov_b32_e32 v230, v145
	v_cvt_pk_bf16_f32 v226, v222, v223
	v_cvt_pk_bf16_f32 v227, v224, v225
	global_store_dwordx2 v230, v[226:227], s[84:85]
	s_waitcnt vmcnt(25)
	v_lshlrev_b32_e32 v218, 16, v154
	v_and_b32_e32 v219, 0xffff0000, v154
	v_lshlrev_b32_e32 v220, 16, v155
	v_and_b32_e32 v221, 0xffff0000, v155
	v_pk_fma_f32 v[222:223], v[118:119], v[218:219], 0 op_sel_hi:[1,1,0]
	v_pk_fma_f32 v[224:225], v[120:121], v[220:221], 0 op_sel_hi:[1,1,0]
	v_lshlrev_b32_e32 v218, 16, v156
	v_and_b32_e32 v219, 0xffff0000, v156
	v_lshlrev_b32_e32 v220, 16, v157
	v_and_b32_e32 v221, 0xffff0000, v157
	v_pk_fma_f32 v[222:223], v[114:115], v[218:219], v[222:223]
	v_pk_fma_f32 v[224:225], v[116:117], v[220:221], v[224:225]
	v_lshlrev_b32_e32 v218, 16, v158
	v_and_b32_e32 v219, 0xffff0000, v158
	v_lshlrev_b32_e32 v220, 16, v159
	v_and_b32_e32 v221, 0xffff0000, v159
	v_pk_fma_f32 v[222:223], v[86:87], v[218:219], v[222:223]
	v_pk_fma_f32 v[224:225], v[88:89], v[220:221], v[224:225]
	v_lshlrev_b32_e32 v218, 16, v160
	v_and_b32_e32 v219, 0xffff0000, v160
	v_lshlrev_b32_e32 v220, 16, v161
	v_and_b32_e32 v221, 0xffff0000, v161
	v_pk_fma_f32 v[222:223], v[82:83], v[218:219], v[222:223]
	v_pk_fma_f32 v[224:225], v[84:85], v[220:221], v[224:225]
	v_add_u32_e32 v231, 0x8000, v145
	v_cvt_pk_bf16_f32 v228, v222, v223
	v_cvt_pk_bf16_f32 v229, v224, v225
	global_store_dwordx2 v231, v[228:229], s[84:85]
	s_waitcnt vmcnt(22)
	v_lshlrev_b32_e32 v218, 16, v162
	v_and_b32_e32 v219, 0xffff0000, v162
	v_lshlrev_b32_e32 v220, 16, v163
	v_and_b32_e32 v221, 0xffff0000, v163
	v_pk_fma_f32 v[222:223], v[110:111], v[218:219], 0 op_sel_hi:[1,1,0]
	v_pk_fma_f32 v[224:225], v[112:113], v[220:221], 0 op_sel_hi:[1,1,0]
	v_lshlrev_b32_e32 v218, 16, v164
	v_and_b32_e32 v219, 0xffff0000, v164
	v_lshlrev_b32_e32 v220, 16, v165
	v_and_b32_e32 v221, 0xffff0000, v165
	v_pk_fma_f32 v[222:223], v[106:107], v[218:219], v[222:223]
	v_pk_fma_f32 v[224:225], v[108:109], v[220:221], v[224:225]
	v_lshlrev_b32_e32 v218, 16, v166
	v_and_b32_e32 v219, 0xffff0000, v166
	v_lshlrev_b32_e32 v220, 16, v167
	v_and_b32_e32 v221, 0xffff0000, v167
	v_pk_fma_f32 v[222:223], v[78:79], v[218:219], v[222:223]
	v_pk_fma_f32 v[224:225], v[80:81], v[220:221], v[224:225]
	v_lshlrev_b32_e32 v218, 16, v168
	v_and_b32_e32 v219, 0xffff0000, v168
	v_lshlrev_b32_e32 v220, 16, v169
	v_and_b32_e32 v221, 0xffff0000, v169
	v_pk_fma_f32 v[222:223], v[74:75], v[218:219], v[222:223]
	v_pk_fma_f32 v[224:225], v[76:77], v[220:221], v[224:225]
	v_add_u32_e32 v230, 0x10000, v145
	v_cvt_pk_bf16_f32 v226, v222, v223
	v_cvt_pk_bf16_f32 v227, v224, v225
	global_store_dwordx2 v230, v[226:227], s[84:85]
	s_waitcnt vmcnt(19)
	v_lshlrev_b32_e32 v218, 16, v202
	v_and_b32_e32 v219, 0xffff0000, v202
	v_lshlrev_b32_e32 v220, 16, v203
	v_and_b32_e32 v221, 0xffff0000, v203
	v_pk_fma_f32 v[222:223], v[102:103], v[218:219], 0 op_sel_hi:[1,1,0]
	v_pk_fma_f32 v[224:225], v[104:105], v[220:221], 0 op_sel_hi:[1,1,0]
	v_lshlrev_b32_e32 v218, 16, v204
	v_and_b32_e32 v219, 0xffff0000, v204
	v_lshlrev_b32_e32 v220, 16, v205
	v_and_b32_e32 v221, 0xffff0000, v205
	v_pk_fma_f32 v[222:223], v[98:99], v[218:219], v[222:223]
	v_pk_fma_f32 v[224:225], v[100:101], v[220:221], v[224:225]
	v_lshlrev_b32_e32 v218, 16, v206
	v_and_b32_e32 v219, 0xffff0000, v206
	v_lshlrev_b32_e32 v220, 16, v207
	v_and_b32_e32 v221, 0xffff0000, v207
	v_pk_fma_f32 v[222:223], v[70:71], v[218:219], v[222:223]
	v_pk_fma_f32 v[224:225], v[72:73], v[220:221], v[224:225]
	v_lshlrev_b32_e32 v218, 16, v208
	v_and_b32_e32 v219, 0xffff0000, v208
	v_lshlrev_b32_e32 v220, 16, v209
	v_and_b32_e32 v221, 0xffff0000, v209
	v_pk_fma_f32 v[222:223], v[66:67], v[218:219], v[222:223]
	v_pk_fma_f32 v[224:225], v[68:69], v[220:221], v[224:225]
	v_add_u32_e32 v231, 0x18000, v145
	v_cvt_pk_bf16_f32 v228, v222, v223
	v_cvt_pk_bf16_f32 v229, v224, v225
	global_store_dwordx2 v231, v[228:229], s[84:85]
	s_waitcnt vmcnt(16)
; __device__ __forceinline__ float lo2f(unsigned w) { return __uint_as_float(w << 16); }
; __device__ __forceinline__ float hi2f(unsigned w) { return __uint_as_float(w & 0xffff0000u); }
; __device__ __forceinline__ float sigm(float x) { return __builtin_amdgcn_rcpf(1.f + __expf(-x)); }
;   __device__ __forceinline__ void operator()(const f32x4 (&acc)[2][2][4][2], const Unit& u, int wr, int wc, int fr, int fq) const {
;     ...
;       const int q = s - 4, bjq = q >> 1, nq = q & 1;
; #pragma unroll
;       for (int ai = 0; ai < 2; ++ai)
; #pragma unroll
;         for (int m = 0; m < 4; ++m) {
;           float o[4] = {0.f, 0.f, 0.f, 0.f};
; #pragma unroll
;           for (int bj = 0; bj < 2; ++bj)
; #pragma unroll
;             for (int n = 0; n < 2; ++n) {
;               const int ib = 2 * bj + n;
;               const uint2 b2 = *(reinterpret_cast<const uint2*>(brs + (size_t)(ib * 16 + (ai * 2 + bjq) * 4 + m) * 512 + tid) + nq);
;               const f32x4 g = acc[ai][bj][m][n];
;               o[0] += sigm(g[0]) * lo2f(b2.x); o[1] += sigm(g[1]) * hi2f(b2.x);
;               o[2] += sigm(g[2]) * lo2f(b2.y); o[3] += sigm(g[3]) * hi2f(b2.y);
;             }
;           const int r = u.pm * 256 + ai * 128 + wr * 64 + m * 16 + fr;
;           const int d = dq * 256 + 64 * q + 16 * wc + 4 * fq;
;           uint2 w; w.x = pack2(o[0], o[1]); w.y = pack2(o[2], o[3]);
;           *reinterpret_cast<uint2*>(ACC + (size_t)r * 1024 + d) = w;
;         }
;     }
	v_lshlrev_b32_e32 v218, 16, v210
	v_and_b32_e32 v219, 0xffff0000, v210
	v_lshlrev_b32_e32 v220, 16, v211
	v_and_b32_e32 v221, 0xffff0000, v211
	v_pk_fma_f32 v[222:223], v[62:63], v[218:219], 0 op_sel_hi:[1,1,0]
	v_pk_fma_f32 v[224:225], v[64:65], v[220:221], 0 op_sel_hi:[1,1,0]
	v_lshlrev_b32_e32 v218, 16, v212
	v_and_b32_e32 v219, 0xffff0000, v212
	v_lshlrev_b32_e32 v220, 16, v213
	v_and_b32_e32 v221, 0xffff0000, v213
	v_pk_fma_f32 v[222:223], v[58:59], v[218:219], v[222:223]
	v_pk_fma_f32 v[224:225], v[60:61], v[220:221], v[224:225]
	v_lshlrev_b32_e32 v218, 16, v214
	v_and_b32_e32 v219, 0xffff0000, v214
	v_lshlrev_b32_e32 v220, 16, v215
	v_and_b32_e32 v221, 0xffff0000, v215
	v_pk_fma_f32 v[222:223], v[30:31], v[218:219], v[222:223]
	v_pk_fma_f32 v[224:225], v[32:33], v[220:221], v[224:225]
	v_lshlrev_b32_e32 v218, 16, v216
	v_and_b32_e32 v219, 0xffff0000, v216
	v_lshlrev_b32_e32 v220, 16, v217
	v_and_b32_e32 v221, 0xffff0000, v217
	v_pk_fma_f32 v[222:223], v[26:27], v[218:219], v[222:223]
	v_pk_fma_f32 v[224:225], v[28:29], v[220:221], v[224:225]
	v_add_u32_e32 v230, 0x40000, v145
	v_cvt_pk_bf16_f32 v226, v222, v223
	v_cvt_pk_bf16_f32 v227, v224, v225
	global_store_dwordx2 v230, v[226:227], s[84:85]
	s_waitcnt vmcnt(13)
	v_lshlrev_b32_e32 v218, 16, v234
	v_and_b32_e32 v219, 0xffff0000, v234
	v_lshlrev_b32_e32 v220, 16, v235
	v_and_b32_e32 v221, 0xffff0000, v235
	v_pk_fma_f32 v[222:223], v[54:55], v[218:219], 0 op_sel_hi:[1,1,0]
	v_pk_fma_f32 v[224:225], v[56:57], v[220:221], 0 op_sel_hi:[1,1,0]
	v_lshlrev_b32_e32 v218, 16, v236
	v_and_b32_e32 v219, 0xffff0000, v236
	v_lshlrev_b32_e32 v220, 16, v237
	v_and_b32_e32 v221, 0xffff0000, v237
	v_pk_fma_f32 v[222:223], v[50:51], v[218:219], v[222:223]
	v_pk_fma_f32 v[224:225], v[52:53], v[220:221], v[224:225]
	v_lshlrev_b32_e32 v218, 16, v238
	v_and_b32_e32 v219, 0xffff0000, v238
	v_lshlrev_b32_e32 v220, 16, v239
	v_and_b32_e32 v221, 0xffff0000, v239
	v_pk_fma_f32 v[222:223], v[22:23], v[218:219], v[222:223]
	v_pk_fma_f32 v[224:225], v[24:25], v[220:221], v[224:225]
	v_lshlrev_b32_e32 v218, 16, v240
	v_and_b32_e32 v219, 0xffff0000, v240
	v_lshlrev_b32_e32 v220, 16, v241
	v_and_b32_e32 v221, 0xffff0000, v241
	v_pk_fma_f32 v[222:223], v[18:19], v[218:219], v[222:223]
	v_pk_fma_f32 v[224:225], v[20:21], v[220:221], v[224:225]
	v_add_u32_e32 v231, 0x48000, v145
	v_cvt_pk_bf16_f32 v228, v222, v223
	v_cvt_pk_bf16_f32 v229, v224, v225
	global_store_dwordx2 v231, v[228:229], s[84:85]
	s_waitcnt vmcnt(10)
	v_lshlrev_b32_e32 v218, 16, v242
	v_and_b32_e32 v219, 0xffff0000, v242
	v_lshlrev_b32_e32 v220, 16, v243
	v_and_b32_e32 v221, 0xffff0000, v243
	v_pk_fma_f32 v[222:223], v[46:47], v[218:219], 0 op_sel_hi:[1,1,0]
	v_pk_fma_f32 v[224:225], v[48:49], v[220:221], 0 op_sel_hi:[1,1,0]
	v_lshlrev_b32_e32 v218, 16, v244
	v_and_b32_e32 v219, 0xffff0000, v244
	v_lshlrev_b32_e32 v220, 16, v245
	v_and_b32_e32 v221, 0xffff0000, v245
	v_pk_fma_f32 v[222:223], v[42:43], v[218:219], v[222:223]
	v_pk_fma_f32 v[224:225], v[44:45], v[220:221], v[224:225]
	v_lshlrev_b32_e32 v218, 16, v246
	v_and_b32_e32 v219, 0xffff0000, v246
	v_lshlrev_b32_e32 v220, 16, v247
	v_and_b32_e32 v221, 0xffff0000, v247
	v_pk_fma_f32 v[222:223], v[14:15], v[218:219], v[222:223]
	v_pk_fma_f32 v[224:225], v[16:17], v[220:221], v[224:225]
	v_lshlrev_b32_e32 v218, 16, v248
	v_and_b32_e32 v219, 0xffff0000, v248
	v_lshlrev_b32_e32 v220, 16, v249
	v_and_b32_e32 v221, 0xffff0000, v249
	v_pk_fma_f32 v[222:223], v[10:11], v[218:219], v[222:223]
	v_pk_fma_f32 v[224:225], v[12:13], v[220:221], v[224:225]
	v_add_u32_e32 v230, 0x50000, v145
	v_cvt_pk_bf16_f32 v226, v222, v223
	v_cvt_pk_bf16_f32 v227, v224, v225
	global_store_dwordx2 v230, v[226:227], s[84:85]
	s_waitcnt vmcnt(7)
	v_lshlrev_b32_e32 v218, 16, v146
	v_and_b32_e32 v219, 0xffff0000, v146
	v_lshlrev_b32_e32 v220, 16, v147
	v_and_b32_e32 v221, 0xffff0000, v147
	v_pk_fma_f32 v[222:223], v[38:39], v[218:219], 0 op_sel_hi:[1,1,0]
	v_pk_fma_f32 v[224:225], v[40:41], v[220:221], 0 op_sel_hi:[1,1,0]
	v_lshlrev_b32_e32 v218, 16, v148
	v_and_b32_e32 v219, 0xffff0000, v148
	v_lshlrev_b32_e32 v220, 16, v149
	v_and_b32_e32 v221, 0xffff0000, v149
	v_pk_fma_f32 v[222:223], v[34:35], v[218:219], v[222:223]
	v_pk_fma_f32 v[224:225], v[36:37], v[220:221], v[224:225]
	v_lshlrev_b32_e32 v218, 16, v150
	v_and_b32_e32 v219, 0xffff0000, v150
	v_lshlrev_b32_e32 v220, 16, v151
	v_and_b32_e32 v221, 0xffff0000, v151
	v_pk_fma_f32 v[222:223], v[6:7], v[218:219], v[222:223]
	v_pk_fma_f32 v[224:225], v[8:9], v[220:221], v[224:225]
	v_lshlrev_b32_e32 v218, 16, v152
	v_and_b32_e32 v219, 0xffff0000, v152
	v_lshlrev_b32_e32 v220, 16, v153
	v_and_b32_e32 v221, 0xffff0000, v153
	v_pk_fma_f32 v[222:223], v[2:3], v[218:219], v[222:223]
	v_pk_fma_f32 v[224:225], v[4:5], v[220:221], v[224:225]
	v_add_u32_e32 v231, 0x58000, v145
	v_cvt_pk_bf16_f32 v228, v222, v223
	v_cvt_pk_bf16_f32 v229, v224, v225
	global_store_dwordx2 v231, v[228:229], s[84:85]
	s_cbranch_execnz .LBB0_1415
